# phase 0 rebalance, second split: one conversion tile per adaLN workgroup, the other 128 workgroups take tiles 384..3023
# baseline (speedup 1.0000x reference)
.LBB0_514:
	v_mov_b32_e32 v2, v0
	s_mov_b32 s13, s2
	s_cmpk_gt_i32 s13, 0xbcf
	s_cbranch_scc1 .LBB0_7
	v_readlane_b32 s0, v252, 2
	v_readlane_b32 s1, v252, 3
	s_load_dword s0, s[0:1], 0x10
	v_lshlrev_b32_e32 v3, 1, v2
	v_add_u32_e32 v23, 0x100, v2
	v_add_u32_e32 v25, 0x200, v2
	v_add_u32_e32 v27, 0x300, v2
	s_waitcnt lgkmcnt(0)
	s_lshr_b32 s0, s0, 16
	s_cmp_lg_u32 s0, 0
	v_add_u32_e32 v29, 0x400, v2
	v_add_u32_e32 v31, 0x500, v2
	v_add_u32_e32 v33, 0x600, v2
	v_add_u32_e32 v35, 0x700, v2
	v_add_u32_e32 v13, 0x800, v2
	v_add_u32_e32 v14, 0x900, v2
	v_add_u32_e32 v15, 0xa00, v2
	v_add_u32_e32 v16, 0xb00, v2
	v_add_u32_e32 v17, 0xc00, v2
	v_add_u32_e32 v18, 0xd00, v2
	v_add_u32_e32 v19, 0xe00, v2
	v_add_u32_e32 v20, 0xf00, v2
	v_and_b32_e32 v4, 63, v2
	v_and_b32_e32 v54, 62, v3
	s_cselect_b64 s[0:1], -1, 0
	v_ashrrev_i32_e32 v5, 6, v2
	v_ashrrev_i32_e32 v6, 6, v23
	v_ashrrev_i32_e32 v7, 6, v25
	v_ashrrev_i32_e32 v8, 6, v27
	v_ashrrev_i32_e32 v9, 6, v29
	v_ashrrev_i32_e32 v10, 6, v31
	v_ashrrev_i32_e32 v11, 6, v33
	v_ashrrev_i32_e32 v12, 6, v35
	v_ashrrev_i32_e32 v13, 6, v13
	v_ashrrev_i32_e32 v14, 6, v14
	v_ashrrev_i32_e32 v15, 6, v15
	v_ashrrev_i32_e32 v16, 6, v16
	v_ashrrev_i32_e32 v17, 6, v17
	v_ashrrev_i32_e32 v18, 6, v18
	v_ashrrev_i32_e32 v19, 6, v19
	v_ashrrev_i32_e32 v20, 6, v20
	v_lshl_add_u32 v52, v4, 2, 0
	s_cmp_lg_u64 s[0:1], 0
	v_mad_u32_u24 v3, v54, s85, 0
	v_mul_lo_u32 v37, v5, s85
	v_mul_lo_u32 v38, v6, s85
	v_mul_lo_u32 v39, v7, s85
	v_mul_lo_u32 v40, v8, s85
	v_mul_lo_u32 v41, v9, s85
	v_mul_lo_u32 v42, v10, s85
	v_mul_lo_u32 v43, v11, s85
	v_mul_lo_u32 v44, v12, s85
	v_mul_lo_u32 v45, v13, s85
	v_mul_lo_u32 v46, v14, s85
	v_mul_lo_u32 v47, v15, s85
	v_mul_lo_u32 v48, v16, s85
	v_mul_lo_u32 v49, v17, s85
	v_mul_lo_u32 v50, v18, s85
	v_mul_lo_u32 v51, v19, s85
	v_mul_lo_u32 v53, v20, s85
	v_ashrrev_i32_e32 v21, 5, v2
	v_ashrrev_i32_e32 v23, 5, v23
	v_ashrrev_i32_e32 v25, 5, v25
	v_ashrrev_i32_e32 v27, 5, v27
	v_ashrrev_i32_e32 v29, 5, v29
	v_ashrrev_i32_e32 v31, 5, v31
	v_ashrrev_i32_e32 v33, 5, v33
	v_ashrrev_i32_e32 v35, 5, v35
	s_addc_u32 s16, s10, 0
	v_lshl_add_u32 v22, v21, 2, v3
	v_lshl_add_u32 v24, v23, 2, v3
	v_lshl_add_u32 v26, v25, 2, v3
	v_lshl_add_u32 v28, v27, 2, v3
	v_lshl_add_u32 v30, v29, 2, v3
	v_lshl_add_u32 v32, v31, 2, v3
	v_lshl_add_u32 v34, v33, 2, v3
	v_lshl_add_u32 v36, v35, 2, v3
	v_add_u32_e32 v37, v52, v37
	v_add_u32_e32 v38, v52, v38
	v_add_u32_e32 v39, v52, v39
	v_add_u32_e32 v40, v52, v40
	v_add_u32_e32 v41, v52, v41
	v_add_u32_e32 v42, v52, v42
	v_add_u32_e32 v43, v52, v43
	v_add_u32_e32 v44, v52, v44
	v_add_u32_e32 v45, v52, v45
	v_add_u32_e32 v46, v52, v46
	v_add_u32_e32 v47, v52, v47
	v_add_u32_e32 v48, v52, v48
	v_add_u32_e32 v49, v52, v49
	v_add_u32_e32 v50, v52, v50
	v_add_u32_e32 v51, v52, v51
	v_add_u32_e32 v52, v52, v53
	v_lshlrev_b32_e32 v130, 1, v54
	s_cmp_eq_u32 s16, 0x200
	s_cbranch_scc0 .Lw0_keep
	s_cmp_lt_u32 s2, 0x180
	s_cbranch_scc0 .Lw0_hi
	s_movk_i32 s16, 0x180
	s_movk_i32 s100, 0x180
	s_branch .Lw0_set
.Lw0_hi:
	s_mov_b32 s13, s2
	s_movk_i32 s16, 0x80
	s_movk_i32 s100, 0xbd0
	s_branch .Lw0_set
